# selected-block tile 0 (always block qt) fetched behind the top-16 ranking loop
# baseline (speedup 1.0000x reference)
; DI int tid_now() { int t = threadIdx.x; asm volatile("" : "+v"(t)); return t; }
; #define PG8_LAS __attribute__((address_space(3)))
;     DI bf16_t* q() const { return (bf16_t*)(ws + WS_Q); }
; DI void unit_nsa(Frame& F, int b, int g, int qt, int tid) {
;     ...
;     { const int tid = tid_now();
;         PG8_LAS float* ib = (PG8_LAS float*)(F.ldsp + A_IMP);
;         const int q = tid >> 3, jj = tid & 7;
;         float mine[8];
; #pragma unroll
;         for (int k = 0; k < 8; ++k) { const int j = 8 * jj + k; const int o = q * A_IMPLD + j;
;             float v = ((ib[o] * ilq[q] + ib[64 * A_IMPLD + o] * ilq[64 + q]) + ib[2 * 64 * A_IMPLD + o] * ilq[128 + q]) + ib[3 * 64 * A_IMPLD + o] * ilq[192 + q];
;             if (j > qt) v = -INFINITY; if (j == 0 || j == qt || j == qt - 1) v = INFINITY; mine[k] = v; }
;         __syncthreads();
.LBB0_1374:
	v_div_scale_f32 v0, s[16:17], v120, v120, 1.0
	s_waitcnt vmcnt(0)
	v_rcp_f32_e32 v2, v0
	v_div_scale_f32 v3, vcc, 1.0, v120, 1.0
	v_fma_f32 v4, -v0, v2, 1.0
	v_fmac_f32_e32 v2, v4, v2
	v_mul_f32_e32 v4, v3, v2
	v_fma_f32 v5, -v0, v4, v3
	v_fmac_f32_e32 v4, v5, v2
	v_fma_f32 v0, -v0, v4, v3
	v_div_fmas_f32 v0, v0, v2, v4
	v_div_fixup_f32 v0, v0, v120, 1.0
	v_cmp_lt_f32_e32 vcc, 0, v120
	s_nop 1
	v_cndmask_b32_e32 v208, 0, v0, vcc
	v_cmp_eq_u32_e32 vcc, 0, v108
	s_and_saveexec_b64 s[16:17], vcc
	v_lshl_add_u32 v0, v109, 2, 0
	v_add_u32_e32 v0, 0x1b610, v0
	ds_write_b32 v0, v208
	s_or_b64 exec, exec, s[16:17]
	s_waitcnt lgkmcnt(0)
	s_barrier
	v_mov_b32_e32 v76, v214
	s_movk_i32 s16, 0x104
	v_ashrrev_i32_e32 v0, 3, v76
	v_mul_lo_u32 v2, v0, s16
	v_and_b32_e32 v78, 7, v76
	v_add_u32_e32 v79, 0, v2
	v_lshl_add_u32 v0, v0, 2, 0
	v_lshl_add_u32 v51, v78, 5, v79
	v_add_u32_e32 v0, 0x1b610, v0
	v_add_u32_e32 v53, 0xb000, v51
	ds_read2st64_b32 v[14:15], v0 offset1:1
	ds_read2st64_b32 v[48:49], v0 offset0:2 offset1:3
	v_add_u32_e32 v2, 0xf100, v51
	v_add_u32_e32 v4, 0x8200, v53
	v_add_u32_e32 v6, 0xc300, v53
	ds_read2_b32 v[2:3], v2 offset1:1
	ds_read2_b32 v[4:5], v4 offset1:1
	ds_read2_b32 v[6:7], v6 offset1:1
	ds_read2_b32 v[8:9], v53 offset1:1
	s_waitcnt lgkmcnt(5)
	v_mov_b32_e32 v50, v15
	s_waitcnt lgkmcnt(3)
	v_pk_mul_f32 v[2:3], v[50:51], v[2:3] op_sel_hi:[0,1]
	v_lshlrev_b32_e32 v0, 3, v78
	s_sub_i32 s22, 62, s97
	s_waitcnt lgkmcnt(0)
	v_pk_fma_f32 v[2:3], v[14:15], v[8:9], v[2:3] op_sel_hi:[0,1,1]
	v_pk_fma_f32 v[2:3], v[48:49], v[4:5], v[2:3] op_sel_hi:[0,1,1]
	v_or_b32_e32 v4, 2, v0
	v_lshl_add_u32 v5, v4, 2, v79
	v_cmp_eq_u32_e64 s[46:47], 0, v78
	v_cmp_eq_u32_e32 vcc, s92, v0
	v_or_b32_e32 v10, 1, v0
	v_add_u32_e32 v12, 0xb000, v5
	s_or_b64 s[16:17], s[46:47], vcc
	v_mov_b32_e32 v52, v49
	v_cmp_eq_u32_e32 vcc, s92, v10
	v_cmp_eq_u32_e64 s[52:53], s22, v10
	v_add_u32_e32 v5, 0xf100, v5
	v_add_u32_e32 v8, 0x8200, v12
	v_add_u32_e32 v10, 0xc300, v12
	v_pk_fma_f32 v[2:3], v[52:53], v[6:7], v[2:3] op_sel_hi:[0,1,1]
	ds_read2_b32 v[6:7], v5 offset1:1
	ds_read2_b32 v[8:9], v8 offset1:1
	ds_read2_b32 v[10:11], v10 offset1:1
	ds_read2_b32 v[12:13], v12 offset1:1
	v_cmp_gt_u32_e64 s[48:49], s92, v0
	s_waitcnt lgkmcnt(3)
	v_pk_mul_f32 v[6:7], v[50:51], v[6:7] op_sel_hi:[0,1]
	v_cmp_ge_u32_e64 s[50:51], s92, v0
	v_cmp_eq_u32_e64 s[54:55], s22, v0
	v_add_u32_e32 v49, 0xb008, v51
	s_waitcnt lgkmcnt(0)
	v_pk_fma_f32 v[6:7], v[14:15], v[12:13], v[6:7] op_sel_hi:[0,1,1]
	v_cndmask_b32_e64 v3, v225, v3, s[48:49]
	v_cndmask_b32_e64 v2, v225, v2, s[50:51]
	s_or_b64 s[54:55], s[16:17], s[54:55]
	s_or_b64 vcc, vcc, s[52:53]
	v_or_b32_e32 v5, 3, v0
	v_pk_fma_f32 v[6:7], v[48:49], v[8:9], v[6:7] op_sel_hi:[0,1,1]
	v_cndmask_b32_e64 v2, v2, v222, s[54:55]
	v_cndmask_b32_e32 v3, v3, v222, vcc
	v_pk_fma_f32 v[6:7], v[52:53], v[10:11], v[6:7] op_sel_hi:[0,1,1]
	v_cmp_lt_u32_e64 s[54:55], s92, v4
	v_cmp_lt_u32_e64 s[52:53], s92, v5
	v_cmp_eq_u32_e32 vcc, s92, v5
	v_cmp_eq_u32_e64 s[58:59], s22, v5
	v_cndmask_b32_e64 v8, v6, v225, s[54:55]
	v_cndmask_b32_e64 v6, v7, v225, s[52:53]
	s_or_b64 vcc, vcc, s[58:59]
	v_cndmask_b32_e32 v7, v6, v222, vcc
	v_or_b32_e32 v6, 4, v0
	v_lshl_add_u32 v9, v6, 2, v79
	v_add_u32_e32 v15, 0xb000, v9
	v_add_u32_e32 v9, 0xf100, v9
	v_add_u32_e32 v12, 0x8200, v15
	v_add_u32_e32 v54, 0xc300, v15
	ds_read2_b32 v[10:11], v9 offset1:1
	ds_read2_b32 v[12:13], v12 offset1:1
	ds_read2_b32 v[54:55], v54 offset1:1
	ds_read2_b32 v[56:57], v15 offset1:1
	v_cmp_eq_u32_e64 s[56:57], s92, v4
	s_waitcnt lgkmcnt(3)
	v_pk_mul_f32 v[10:11], v[50:51], v[10:11] op_sel_hi:[0,1]
	v_cmp_eq_u32_e64 s[60:61], s22, v4
	s_or_b64 vcc, s[56:57], s[60:61]
	s_waitcnt lgkmcnt(0)
	v_pk_fma_f32 v[10:11], v[14:15], v[56:57], v[10:11] op_sel_hi:[0,1,1]
	v_or_b32_e32 v9, 5, v0
	v_pk_fma_f32 v[10:11], v[48:49], v[12:13], v[10:11] op_sel_hi:[0,1,1]
	v_cndmask_b32_e32 v8, v8, v222, vcc
	v_pk_fma_f32 v[10:11], v[52:53], v[54:55], v[10:11] op_sel_hi:[0,1,1]
	v_cmp_lt_u32_e64 s[58:59], s92, v6
	v_cmp_lt_u32_e64 s[56:57], s92, v9
	v_cmp_eq_u32_e32 vcc, s92, v9
	v_cmp_eq_u32_e64 s[62:63], s22, v9
	v_cndmask_b32_e64 v12, v10, v225, s[58:59]
	v_cndmask_b32_e64 v10, v11, v225, s[56:57]
	s_or_b64 vcc, vcc, s[62:63]
	v_cndmask_b32_e32 v11, v10, v222, vcc
	v_or_b32_e32 v10, 6, v0
	v_lshl_add_u32 v13, v10, 2, v79
	v_add_u32_e32 v15, 0xb000, v13
	v_add_u32_e32 v13, 0xf100, v13
	v_add_u32_e32 v56, 0x8200, v15
	v_add_u32_e32 v58, 0xc300, v15
	ds_read2_b32 v[54:55], v13 offset1:1
	ds_read2_b32 v[56:57], v56 offset1:1
	ds_read2_b32 v[58:59], v58 offset1:1
	ds_read2_b32 v[60:61], v15 offset1:1
	v_add_u32_e32 v62, 0xb010, v51
	v_add_u32_e32 v63, 0xb018, v51
	s_waitcnt lgkmcnt(3)
	v_pk_mul_f32 v[50:51], v[50:51], v[54:55] op_sel_hi:[0,1]
	v_cmp_eq_u32_e64 s[60:61], s92, v6
	v_cmp_eq_u32_e64 s[64:65], s22, v6
	s_waitcnt lgkmcnt(0)
	v_pk_fma_f32 v[14:15], v[14:15], v[60:61], v[50:51] op_sel_hi:[0,1,1]
	s_or_b64 vcc, s[60:61], s[64:65]
	v_or_b32_e32 v13, 7, v0
	v_pk_fma_f32 v[14:15], v[48:49], v[56:57], v[14:15] op_sel_hi:[0,1,1]
	v_cndmask_b32_e32 v12, v12, v222, vcc
	v_pk_fma_f32 v[14:15], v[52:53], v[58:59], v[14:15] op_sel_hi:[0,1,1]
	v_cmp_lt_u32_e64 s[60:61], s92, v13
	v_cmp_eq_u32_e32 vcc, s92, v13
	v_cmp_eq_u32_e64 s[66:67], s22, v13
	v_cmp_lt_u32_e64 s[62:63], s92, v10
	v_cndmask_b32_e64 v15, v15, v225, s[60:61]
	v_cmp_eq_u32_e64 s[64:65], s92, v10
	v_cmp_eq_u32_e64 s[68:69], s22, v10
	s_or_b64 vcc, vcc, s[66:67]
	v_cndmask_b32_e64 v14, v14, v225, s[62:63]
	v_cndmask_b32_e32 v15, v15, v222, vcc
	s_or_b64 vcc, s[64:65], s[68:69]
	v_cndmask_b32_e32 v14, v14, v222, vcc
	s_barrier
;     DI bf16_t* q() const { return (bf16_t*)(ws + WS_Q); }
; template <bool MLA> DI void tile_gload(TileRegs& R, const bf16_t* kp, size_t kst, const bf16_t* vp, size_t vst, const bf16_t* k2p, int kb, int tid) {
;     const int key = tid >> 3, c = tid & 7;
;     R.k = *(const u32x4*)(kp + (size_t)(kb + key) * kst + 8 * c);
;     R.v = *(const u32x4*)(vp + (size_t)(kb + (tid & 63)) * vst + 8 * (tid >> 6));
;     if (MLA) R.k2 = *(const u32x4*)(k2p + (size_t)(kb + ((tid & 255) >> 2)) * 32 + 8 * (tid & 3));
; }
; DI void unit_nsa(Frame& F, int b, int g, int qt, int tid) {
;     ...
; #pragma unroll
;         for (int k = 0; k < 8; ++k) ib[q * A_IMPLD + 8 * jj + k] = mine[k];
;         __syncthreads();
;         int rank[8];
; #pragma unroll
;         for (int k = 0; k < 8; ++k) rank[k] = 0;
;         float vnx = ib[q * A_IMPLD];
;         for (int j2 = 0; j2 <= qt; ++j2) { const float v2 = vnx; vnx = ib[q * A_IMPLD + (j2 < qt ? j2 + 1 : j2)];
; #pragma unroll
;             for (int k = 0; k < 8; ++k) rank[k] += (v2 > mine[k] || (v2 == mine[k] && j2 < 8 * jj + k)) ? 1 : 0; }
	ds_write2_b32 v53, v2, v3 offset1:1
	ds_write2_b32 v49, v8, v7 offset1:1
	ds_write2_b32 v62, v12, v11 offset1:1
	ds_write2_b32 v63, v14, v15 offset1:1
	s_waitcnt lgkmcnt(0)
	s_barrier
	ds_read_b32 v80, v79 offset:45056
	v_readlane_b32 s24, v254, 44
	v_readlane_b32 s25, v254, 45
	s_lshl_b32 s16, s43, 24
	s_add_u32 s24, s24, s16
	s_addc_u32 s25, s25, 0
	s_lshl_b32 s16, s42, 7
	s_add_u32 s24, s24, s16
	s_addc_u32 s25, s25, 0
	v_ashrrev_i32_e32 v250, 3, v214
	v_add_u32_e32 v236, s96, v250
	v_ashrrev_i32_e32 v237, 31, v236
	v_lshlrev_b64 v[236:237], 12, v[236:237]
	v_lshlrev_b32_e32 v238, 4, v214
	v_and_b32_e32 v238, 0x70, v238
	v_mov_b32_e32 v239, 0
	v_lshl_add_u64 v[236:237], s[24:25], 0, v[236:237]
	v_lshl_add_u64 v[236:237], v[236:237], 0, v[238:239]
	v_and_b32_e32 v248, 63, v214
	v_or_b32_e32 v248, s96, v248
	v_lshlrev_b32_e32 v248, 12, v248
	v_mov_b32_e32 v249, 0
	v_and_b32_e32 v250, -8, v250
	v_lshlrev_b32_e32 v250, 1, v250
	v_mov_b32_e32 v251, 0
	v_lshl_add_u64 v[248:249], s[24:25], 0, v[248:249]
	v_lshl_add_u64 v[248:249], v[248:249], 0, v[250:251]
	global_load_dwordx4 v[240:243], v[236:237], off offset:2816
	global_load_dwordx4 v[244:247], v[248:249], off offset:3584
	s_sub_i32 s22, 64, s97
	s_mov_b32 s23, 0
	v_mov_b32_e32 v55, 0
	v_mov_b32_e32 v54, 0
	v_mov_b32_e32 v53, 0
	v_mov_b32_e32 v52, 0
	v_mov_b32_e32 v51, 0
	v_mov_b32_e32 v50, 0
	v_mov_b32_e32 v49, 0
	v_mov_b32_e32 v48, 0
	v_cmp_eq_u32_e64 s[16:17], v2, v3
	v_cmp_eq_u32_e64 s[24:25], v2, v8
	v_cmp_eq_u32_e64 s[68:69], v3, v8
	v_cmp_eq_u32_e32 vcc, v2, v7
	v_addc_co_u32_e64 v54, s[16:17], 0, v54, s[16:17]
	v_addc_co_u32_e64 v53, s[24:25], 0, v53, s[24:25]
	v_addc_co_u32_e64 v53, s[68:69], 0, v53, s[68:69]
	v_addc_co_u32_e32 v52, vcc, 0, v52, vcc
	v_cmp_eq_u32_e64 s[16:17], v3, v7
	v_cmp_eq_u32_e64 s[24:25], v8, v7
	v_cmp_eq_u32_e64 s[68:69], v2, v12
	v_cmp_eq_u32_e32 vcc, v3, v12
	v_addc_co_u32_e64 v52, s[16:17], 0, v52, s[16:17]
	v_addc_co_u32_e64 v52, s[24:25], 0, v52, s[24:25]
	v_addc_co_u32_e64 v51, s[68:69], 0, v51, s[68:69]
	v_addc_co_u32_e32 v51, vcc, 0, v51, vcc
	v_cmp_eq_u32_e64 s[16:17], v8, v12
	v_cmp_eq_u32_e64 s[24:25], v7, v12
	v_cmp_eq_u32_e64 s[68:69], v2, v11
	v_cmp_eq_u32_e32 vcc, v3, v11
	v_addc_co_u32_e64 v51, s[16:17], 0, v51, s[16:17]
	v_addc_co_u32_e64 v51, s[24:25], 0, v51, s[24:25]
	v_addc_co_u32_e64 v50, s[68:69], 0, v50, s[68:69]
	v_addc_co_u32_e32 v50, vcc, 0, v50, vcc
	v_cmp_eq_u32_e64 s[16:17], v8, v11
	v_cmp_eq_u32_e64 s[24:25], v7, v11
	v_cmp_eq_u32_e64 s[68:69], v12, v11
	v_cmp_eq_u32_e32 vcc, v2, v14
	v_addc_co_u32_e64 v50, s[16:17], 0, v50, s[16:17]
	v_addc_co_u32_e64 v50, s[24:25], 0, v50, s[24:25]
	v_addc_co_u32_e64 v50, s[68:69], 0, v50, s[68:69]
	v_addc_co_u32_e32 v49, vcc, 0, v49, vcc
	v_cmp_eq_u32_e64 s[16:17], v3, v14
	v_cmp_eq_u32_e64 s[24:25], v8, v14
	v_cmp_eq_u32_e64 s[68:69], v7, v14
	v_cmp_eq_u32_e32 vcc, v12, v14
	v_addc_co_u32_e64 v49, s[16:17], 0, v49, s[16:17]
	v_addc_co_u32_e64 v49, s[24:25], 0, v49, s[24:25]
	v_addc_co_u32_e64 v49, s[68:69], 0, v49, s[68:69]
	v_addc_co_u32_e32 v49, vcc, 0, v49, vcc
	v_cmp_eq_u32_e64 s[16:17], v11, v14
	v_cmp_eq_u32_e64 s[24:25], v2, v15
	v_cmp_eq_u32_e64 s[68:69], v3, v15
	v_cmp_eq_u32_e32 vcc, v8, v15
	v_addc_co_u32_e64 v49, s[16:17], 0, v49, s[16:17]
	v_addc_co_u32_e64 v48, s[24:25], 0, v48, s[24:25]
	v_addc_co_u32_e64 v48, s[68:69], 0, v48, s[68:69]
	v_addc_co_u32_e32 v48, vcc, 0, v48, vcc
	v_cmp_eq_u32_e64 s[16:17], v7, v15
	v_cmp_eq_u32_e64 s[24:25], v12, v15
	v_cmp_eq_u32_e64 s[68:69], v11, v15
	v_cmp_eq_u32_e32 vcc, v14, v15
	v_addc_co_u32_e64 v48, s[16:17], 0, v48, s[16:17]
	v_addc_co_u32_e64 v48, s[24:25], 0, v48, s[24:25]
	v_addc_co_u32_e64 v48, s[68:69], 0, v48, s[68:69]
	v_addc_co_u32_e32 v48, vcc, 0, v48, vcc

; DI int tid_now() { int t = threadIdx.x; asm volatile("" : "+v"(t)); return t; }
;     DI float* h() const { return (float*)(__attribute__((address_space(1))) float*)kp->out; }
; template <bool MLA, class TL, class CF>
; DI void att_pipe(lbf KB, lbf VB, const bf16_t* kp, size_t kst, const bf16_t* vp, size_t vst, const bf16_t* k2p, const TL& tl, CF& cf, int) {
;     ...
;     TileRegs R0, R1; tile_gload<MLA>(R0, kp, kst, vp, vst, k2p, kb, tid);
;     int nk = tl.next(kb);
;     tile_gload<MLA>(R1, kp, kst, vp, vst, k2p, nk >= 0 ? nk : kb, tid);
;     __syncthreads();
;     tile_lstore<MLA>(R0, KB, VB, tid);
;     __syncthreads();
; DI void unit_nsa(Frame& F, int b, int g, int qt, int tid) {
;     ...
;     const unsigned long long qsel = (unsigned long long)selm[2 * ql] | ((unsigned long long)selm[2 * ql + 1] << 32);
;     const unsigned long long umask = (unsigned long long)uni[0] | ((unsigned long long)uni[1] << 32);
;     zero_o(O); m = -1e30f; l = 0.f;
;     ...
;     __builtin_amdgcn_sched_barrier(0);
;     { const int r = tid_now() & 31, h = (tid_now() >> 5) & 1; CfNsa<true> cs{Q, O, m, l, t, r, h, sl2, qsel}; att_pipe<false>(KB, VB, zb + Z_KS + g * 64, ZP, zb + Z_VS + g * 64, ZP, nullptr, TlMaskDesc{umask}, cs, tid); }
.LBB0_1425:
	s_or_b64 exec, exec, s[16:17]
	s_lshl_b32 s16, s43, 24
	v_readlane_b32 s22, v254, 44
	v_readlane_b32 s23, v254, 45
	s_add_u32 s22, s22, s16
	s_addc_u32 s23, s23, 0
	s_add_i32 s16, 0, 0x1b600
	v_lshl_add_u32 v0, v106, 3, 0
	s_waitcnt lgkmcnt(1)
	v_mov_b32_e32 v2, s16
	s_waitcnt lgkmcnt(0)
	s_barrier
	ds_read_b64 v[4:5], v2
	v_add_u32_e32 v0, 0x1b400, v0
	ds_read_b64 v[120:121], v0
	s_waitcnt lgkmcnt(1)
	v_readfirstlane_b32 s48, v4
	v_readfirstlane_b32 s49, v5
	v_cmp_ne_u64_e32 vcc, 0, v[4:5]
	v_mov_b32_e32 v2, v214
	v_mov_b32_e32 v3, v214
	s_lshl_b32 s42, s42, 6
	s_cbranch_vccz .LBB0_1509
	s_lshl_b32 s16, s42, 1
	s_add_u32 s16, s22, s16
	s_flbit_i32_b64 s46, s[48:49]
	s_addc_u32 s17, s23, 0
	s_lshl_b32 s24, s46, 6
	s_xor_b32 s43, s24, 0xfc0
	s_lshr_b32 s24, s43, 6
	s_lshl_b64 s[24:25], -1, s24
	s_andn2_b64 s[24:25], s[48:49], s[24:25]
	s_cmp_lg_u32 s46, 63
	s_cselect_b32 s25, s25, 0
	s_cselect_b32 s24, s24, 0
	s_flbit_i32_b64 s46, s[24:25]
	v_mov_b32_e32 v52, v214
	s_lshl_b32 s46, s46, 6
	s_xor_b32 s46, s46, 0xfc0
	v_ashrrev_i32_e32 v136, 3, v52
	v_add_u32_e32 v4, s43, v136
	v_and_b32_e32 v137, 63, v52
	s_cmp_eq_u64 s[24:25], 0
	v_ashrrev_i32_e32 v5, 31, v4
	v_or_b32_e32 v6, s43, v137
	v_and_b32_e32 v12, -8, v136
	s_cselect_b32 s24, s43, s46
	v_lshlrev_b64 v[4:5], 12, v[4:5]
	v_lshlrev_b32_e32 v0, 4, v52
	v_lshlrev_b32_e32 v6, 12, v6
	v_mov_b32_e32 v7, v1
	v_ashrrev_i32_e32 v13, 31, v12
	v_add_u32_e32 v48, s24, v136
	v_lshl_add_u64 v[4:5], s[16:17], 0, v[4:5]
	v_and_b32_e32 v0, 0x70, v0
	v_lshl_add_u64 v[6:7], s[16:17], 0, v[6:7]
	v_lshlrev_b64 v[14:15], 1, v[12:13]
	v_ashrrev_i32_e32 v49, 31, v48
	v_lshl_add_u64 v[4:5], v[4:5], 0, v[0:1]
	v_lshl_add_u64 v[8:9], v[6:7], 0, v[14:15]
	v_lshlrev_b64 v[48:49], 12, v[48:49]
	v_or_b32_e32 v13, s24, v137
	s_nop 0
	s_nop 0
	s_nop 0
	v_lshl_add_u64 v[48:49], s[16:17], 0, v[48:49]
	v_lshlrev_b32_e32 v50, 12, v13
	v_mov_b32_e32 v51, v1
	v_lshl_add_u64 v[48:49], v[48:49], 0, v[0:1]
	v_lshl_add_u64 v[50:51], s[16:17], 0, v[50:51]
	v_lshl_add_u64 v[50:51], v[50:51], 0, v[14:15]
	global_load_dwordx4 v[116:119], v[48:49], off offset:2816
	global_load_dwordx4 v[112:115], v[50:51], off offset:3584
	v_bfe_u32 v3, v3, 5, 1
	v_and_b32_e32 v2, 31, v2
	v_mul_u32_u24_e32 v13, 0x90, v2
	v_sub_u32_e32 v138, v205, v2
	v_lshlrev_b32_e32 v139, 2, v3
	v_lshlrev_b32_e32 v2, 4, v3
	v_and_b32_e32 v3, 51, v52
	v_lshlrev_b32_e32 v48, 2, v52
	v_and_b32_e32 v49, 8, v52
	s_movk_i32 s24, 0x90
	v_lshl_add_u32 v3, v3, 1, 0
	v_and_b32_e32 v48, 16, v48
	v_or_b32_e32 v51, 7, v136
	v_mul_lo_u32 v50, v136, s24
	v_add3_u32 v142, v3, v48, v49
	v_mul_lo_u32 v143, v12, s24
	v_mul_lo_u32 v160, v51, s24
	v_add3_u32 v141, 0, v50, v0
	v_lshl_add_u64 v[122:123], s[16:17], 0, v[0:1]
	v_add_u32_e32 v0, v142, v143
	v_add_u32_e32 v3, v142, v160
	v_lshl_add_u64 v[124:125], s[16:17], 0, v[14:15]
	v_mov_b32_e32 v14, v1
	v_mov_b32_e32 v15, v1
	s_waitcnt lgkmcnt(0)
	s_barrier
	v_add3_u32 v161, 0, v13, v2
	v_mov_b32_e32 v2, v1
	v_mov_b32_e32 v12, v1
	v_mov_b32_e32 v13, v1
	s_mov_b32 s52, 0
	v_mov_b32_e32 v187, v186
	v_sub_u32_e32 v140, v139, v205
	s_cselect_b32 s16, -1, s46
	v_mov_b32_e32 v209, 0
	v_mov_b32_e32 v162, 0xf149f2ca
	s_waitcnt vmcnt(3)
	ds_write_b128 v141, v[240:243]
	s_waitcnt vmcnt(2)
	ds_write_b16 v0, v244 offset:26624
	ds_write_b16_d16_hi v0, v244 offset:26768
	ds_write_b16 v0, v245 offset:26912
	ds_write_b16_d16_hi v0, v245 offset:27056
	ds_write_b16 v0, v246 offset:27200
	ds_write_b16_d16_hi v0, v246 offset:27344
	ds_write_b16 v0, v247 offset:27488
	ds_write_b16_d16_hi v3, v247 offset:26624
	v_mov_b32_e32 v0, v1
	v_mov_b32_e32 v3, v1
	v_mov_b32_e32 v4, v1
	v_mov_b32_e32 v5, v1
	v_mov_b32_e32 v6, v1
	v_mov_b32_e32 v7, v1
	v_mov_b32_e32 v8, v1
	v_mov_b32_e32 v9, v1
	v_mov_b32_e32 v10, v1
	v_mov_b32_e32 v11, v1
	v_mov_b64_e32 v[78:79], v[14:15]
	v_mov_b64_e32 v[62:63], v[14:15]
	v_mov_b64_e32 v[76:77], v[12:13]
	v_mov_b64_e32 v[74:75], v[10:11]
	v_mov_b64_e32 v[72:73], v[8:9]
	v_mov_b64_e32 v[70:71], v[6:7]
	v_mov_b64_e32 v[68:69], v[4:5]
	v_mov_b64_e32 v[66:67], v[2:3]
	v_mov_b64_e32 v[64:65], v[0:1]
	v_mov_b64_e32 v[60:61], v[12:13]
	v_mov_b64_e32 v[58:59], v[10:11]
	v_mov_b64_e32 v[56:57], v[8:9]
	v_mov_b64_e32 v[54:55], v[6:7]
	v_mov_b64_e32 v[52:53], v[4:5]
	v_mov_b64_e32 v[50:51], v[2:3]
	v_mov_b64_e32 v[48:49], v[0:1]
	s_waitcnt lgkmcnt(0)
	s_barrier
	s_branch .LBB0_1428
